# P2 slices: g_low tail reads its four rstd values with one dwordx4 instead of four dependent loads
# speedup vs baseline: 1.0041x; 1.0041x over previous
.LBB0_220:
	s_andn2_b64 vcc, exec, s[0:1]
	s_waitcnt lgkmcnt(0)
	s_barrier
	s_cbranch_vccnz .LBB0_222
	v_add_u32_e32 v12, s4, v136
	v_ashrrev_i32_e32 v13, 31, v12
	v_lshl_add_u64 v[8:9], v[12:13], 2, s[20:21]
	global_load_dwordx4 v[184:187], v[8:9], off
	ds_read_b128 v[8:11], v7
	v_lshlrev_b32_e32 v6, 2, v6
	v_mov_b32_e32 v7, 0
	v_lshl_add_u64 v[6:7], s[16:17], 0, v[6:7]
	v_or_b32_e32 v14, 1, v12
	v_lshlrev_b64 v[16:17], 6, v[12:13]
	s_waitcnt lgkmcnt(0)
	v_add_f32_e32 v2, v2, v8
	v_ashrrev_i32_e32 v15, 31, v14
	v_lshl_add_u64 v[16:17], v[6:7], 0, v[16:17]
	v_lshl_add_u64 v[18:19], v[14:15], 2, s[20:21]
	v_lshlrev_b64 v[14:15], 6, v[14:15]
	v_add_f32_e32 v3, v3, v9
	v_lshl_add_u64 v[14:15], v[6:7], 0, v[14:15]
	v_add_f32_e32 v4, v4, v10
	v_add_f32_e32 v5, v5, v11
	s_waitcnt vmcnt(0)
	v_mul_f32_e32 v2, v2, v184
	global_store_dword v[16:17], v2, off
	s_nop 1
	v_mov_b32_e32 v2, v185
	v_or_b32_e32 v16, 2, v12
	v_ashrrev_i32_e32 v17, 31, v16
	v_lshl_add_u64 v[18:19], v[16:17], 2, s[20:21]
	v_lshlrev_b64 v[8:9], 6, v[16:17]
	v_lshl_add_u64 v[8:9], v[6:7], 0, v[8:9]
	v_mul_f32_e32 v2, v3, v2
	global_store_dword v[14:15], v2, off
	s_nop 1
	v_mov_b32_e32 v14, v186
	v_or_b32_e32 v2, 3, v12
	v_ashrrev_i32_e32 v3, 31, v2
	v_lshl_add_u64 v[12:13], v[2:3], 2, s[20:21]
	v_lshlrev_b64 v[2:3], 6, v[2:3]
	v_lshl_add_u64 v[2:3], v[6:7], 0, v[2:3]
	v_mul_f32_e32 v4, v4, v14
	global_store_dword v[8:9], v4, off
	s_nop 1
	v_mov_b32_e32 v4, v187
	v_mul_f32_e32 v4, v5, v4
	global_store_dword v[2:3], v4, off

.LBB0_332:
	s_andn2_b64 vcc, exec, s[0:1]
	s_waitcnt lgkmcnt(0)
	s_barrier
	s_cbranch_vccnz .LBB0_334
	v_add_u32_e32 v12, s6, v136
	v_ashrrev_i32_e32 v13, 31, v12
	v_lshl_add_u64 v[8:9], v[12:13], 2, s[20:21]
	global_load_dwordx4 v[184:187], v[8:9], off
	ds_read_b128 v[8:11], v7
	v_lshlrev_b32_e32 v6, 2, v6
	v_mov_b32_e32 v7, 0
	v_lshl_add_u64 v[6:7], s[16:17], 0, v[6:7]
	v_or_b32_e32 v14, 1, v12
	v_lshlrev_b64 v[16:17], 6, v[12:13]
	s_waitcnt lgkmcnt(0)
	v_add_f32_e32 v2, v2, v8
	v_ashrrev_i32_e32 v15, 31, v14
	v_lshl_add_u64 v[16:17], v[6:7], 0, v[16:17]
	v_lshl_add_u64 v[18:19], v[14:15], 2, s[20:21]
	v_lshlrev_b64 v[14:15], 6, v[14:15]
	v_add_f32_e32 v3, v3, v9
	v_lshl_add_u64 v[14:15], v[6:7], 0, v[14:15]
	v_add_f32_e32 v4, v4, v10
	v_add_f32_e32 v5, v5, v11
	s_waitcnt vmcnt(0)
	v_mul_f32_e32 v2, v2, v184
	global_store_dword v[16:17], v2, off
	s_nop 1
	v_mov_b32_e32 v2, v185
	v_or_b32_e32 v16, 2, v12
	v_ashrrev_i32_e32 v17, 31, v16
	v_lshl_add_u64 v[18:19], v[16:17], 2, s[20:21]
	v_lshlrev_b64 v[8:9], 6, v[16:17]
	v_lshl_add_u64 v[8:9], v[6:7], 0, v[8:9]
	v_mul_f32_e32 v2, v3, v2
	global_store_dword v[14:15], v2, off
	s_nop 1
	v_mov_b32_e32 v14, v186
	v_or_b32_e32 v2, 3, v12
	v_ashrrev_i32_e32 v3, 31, v2
	v_lshl_add_u64 v[12:13], v[2:3], 2, s[20:21]
	v_lshlrev_b64 v[2:3], 6, v[2:3]
	v_lshl_add_u64 v[2:3], v[6:7], 0, v[2:3]
	v_mul_f32_e32 v4, v4, v14
	global_store_dword v[8:9], v4, off
	s_nop 1
	v_mov_b32_e32 v4, v187
	v_mul_f32_e32 v4, v5, v4
	global_store_dword v[2:3], v4, off
